# A/E: first K-tile fragment ds_reads hoisted above the unit-header scalar block (LDS latency overlaps next-unit index math)
# speedup vs baseline: 1.0059x; 1.0010x over previous
.LBB0_395:
	v_add_u32_e32 v222, 0x10000, v206
	ds_read_b128 v[136:139], v222
	ds_read_b128 v[140:143], v222 offset:1024
	ds_read_b128 v[144:147], v222 offset:2048
	ds_read_b128 v[148:151], v222 offset:3072
	v_add_u32_e32 v223, 0x14000, v206
	ds_read_b128 v[152:155], v223
	ds_read_b128 v[156:159], v223 offset:1024
	ds_read_b128 v[160:163], v223 offset:2048
	ds_read_b128 v[164:167], v223 offset:3072
	ds_read_b128 v[168:171], v213
	ds_read_b128 v[172:175], v213 offset:1024
	ds_read_b128 v[176:179], v213 offset:2048
	ds_read_b128 v[194:197], v213 offset:3072
	ds_read_b128 v[198:201], v213 offset:4096
	ds_read_b128 v[202:205], v213 offset:5120
	ds_read_b128 v[216:219], v213 offset:6144
	ds_read_b128 v[220:223], v213 offset:7168
	s_add_i32 s46, s29, 1
	s_mul_i32 s4, s46, s33
	s_add_i32 s4, s4, s61
	s_cmpk_lt_i32 s4, 0x4a4
	s_cselect_b64 s[2:3], -1, 0
	s_cmpk_gt_i32 s4, 0x4a3
	s_cselect_b64 s[20:21], -1, 0
	v_readlane_b32 s14, v250, 51
	s_and_b64 vcc, exec, s[20:21]
	v_readlane_b32 s15, v250, 52
	s_cbranch_vccnz .LBB0_401
	s_ashr_i32 s1, s4, 31
	s_lshr_b32 s1, s1, 29
	s_add_i32 s1, s4, s1
	s_and_b32 s5, s1, -8
	s_sub_i32 s4, s4, s5
	s_cmp_gt_i32 s4, 3
	s_mov_b64 s[10:11], -1
	s_cbranch_scc0 .LBB0_398
	s_mul_i32 s5, s4, 0x94
	s_add_i32 s5, s5, 4
	s_mov_b64 s[10:11], 0

.Lpeel_a:
	s_add_u32 s10, s54, s8
	s_addc_u32 s11, s55, s9
	s_add_u32 s10, s10, 0x100
	s_addc_u32 s11, s11, 0
	s_add_u32 s18, s78, s8
	s_addc_u32 s24, s1, s9
	s_add_i32 s25, 0, 0x10000
	s_cmpk_eq_i32 s8, 0x700
	s_cselect_b32 s15, s4, s11
	s_cselect_b32 s14, s5, s10
	s_cselect_b32 s11, s12, s24
	s_cselect_b32 s10, s13, s18
	s_add_i32 s18, 0, 0x14000
	v_lshl_add_u64 v[224:225], v[132:133], 0, s[8:9]
	s_add_i32 m0, s51, 0xc000
	global_load_lds_dwordx4 v[224:225], off
	v_lshl_add_u64 v[224:225], v[134:135], 0, s[8:9]
	s_add_i32 m0, s51, 0xe000
	s_nop 0
	global_load_lds_dwordx4 v[224:225], off
	s_cmp_eq_u32 s100, 0
	s_cbranch_scc1 .Lvrp_a1_strict
	s_waitcnt vmcnt(24)
	s_sub_u32 s100, s100, 1
	s_branch .Lvrp_a1_done

.LBB0_1756:
	v_add_u32_e32 v196, 0x10000, v249
	ds_read_b128 v[134:137], v196
	ds_read_b128 v[138:141], v196 offset:1024
	ds_read_b128 v[142:145], v196 offset:2048
	ds_read_b128 v[146:149], v196 offset:3072
	v_add_u32_e32 v197, 0x14000, v249
	ds_read_b128 v[150:153], v197
	ds_read_b128 v[154:157], v197 offset:1024
	ds_read_b128 v[158:161], v197 offset:2048
	ds_read_b128 v[162:165], v197 offset:3072
	ds_read_b128 v[166:169], v234
	ds_read_b128 v[170:173], v234 offset:1024
	ds_read_b128 v[174:177], v234 offset:2048
	ds_read_b128 v[178:181], v234 offset:3072
	ds_read_b128 v[182:185], v234 offset:4096
	ds_read_b128 v[186:189], v234 offset:5120
	ds_read_b128 v[190:193], v234 offset:6144
	ds_read_b128 v[194:197], v234 offset:7168
	v_readlane_b32 s1, v251, 17
	s_add_i32 s1, s1, 1
	s_mul_i32 s2, s1, s33
	v_readlane_b32 s3, v251, 19
	s_add_i32 s2, s2, s3
	s_cmpk_lt_i32 s2, 0x5ac
	s_cselect_b64 s[52:53], -1, 0
	s_cmpk_gt_i32 s2, 0x5ab
	s_cselect_b64 s[24:25], -1, 0
	v_readlane_b32 s10, v250, 51
	s_and_b64 vcc, exec, s[24:25]
	v_readlane_b32 s11, v250, 52
	s_cbranch_vccnz .LBB0_1762
	s_ashr_i32 s3, s2, 31
	s_lshr_b32 s3, s3, 29
	s_add_i32 s4, s2, s3
	s_and_b32 s3, s4, -8
	s_sub_i32 s5, s2, s3
	s_cmp_gt_i32 s5, 3
	s_mov_b64 s[2:3], -1
	s_cbranch_scc0 .LBB0_1759
	s_mul_i32 s2, s5, 0xb5
	s_add_i32 s8, s2, 4
	s_mov_b64 s[2:3], 0

.Lpeel_e:
	s_add_u32 s17, s48, s38
	s_addc_u32 s29, s49, s39
	s_add_u32 s10, s17, 0x100
	s_addc_u32 s11, s29, 0
	s_add_u32 s14, s20, s38
	s_addc_u32 s15, s21, s39
	s_add_u32 s14, s14, 0x100
	s_addc_u32 s15, s15, 0
	s_cmp_eq_u32 s13, 12
	s_cselect_b32 s40, s5, s10
	s_cselect_b32 s41, s4, s11
	s_cselect_b32 s14, s12, s14
	s_cselect_b32 s15, s9, s15
	s_add_u32 s10, s40, 0x80
	s_addc_u32 s11, s41, 0
	s_add_u32 s28, s17, 0x40080
	s_addc_u32 s29, s29, 0
	s_mov_b32 m0, s80
	s_nop 0
	global_load_lds_dwordx4 v1, s[28:29]
	s_nop 0
	s_mov_b32 m0, s81
	s_nop 0
	global_load_lds_dwordx4 v239, s[28:29]
	s_cmp_eq_u32 s100, 0
	s_cbranch_scc1 .Lvrp_e1_strict
	s_waitcnt vmcnt(16)
	s_sub_u32 s100, s100, 1
	s_branch .Lvrp_e1_done
